# K-loops: redundant lgkmcnt(0) after the load-segment barrier removed
# speedup vs baseline: 1.0038x; 1.0038x over previous
; #define PG8_STAGE(bufoff, gbase, voff) do { _Pragma("unroll") for (int _i = 0; _i < 2; ++_i) \
;         __builtin_amdgcn_global_load_lds((const unsigned*)((const char*)(gbase) + (voff)[_i]), (PG8_LAS unsigned*)(lds + (bufoff) + ldsw + _i * 8192), 16, 0, 0); } while (0)
; #define PG8_LDA(dst, b, h) do { _Pragma("unroll") for (int m = 0; m < 4; ++m) _Pragma("unroll") for (int k = 0; k < 2; ++k) dst[m][k] = *(const PG8_LAS bf16x8*)(lds + PG8_SA(b, h) + aoff + m * 2048 + k * 1024); } while (0)
; #define PG8_LDB(dst, b, h) do { _Pragma("unroll") for (int n = 0; n < 2; ++n) _Pragma("unroll") for (int k = 0; k < 2; ++k) dst[n][k] = *(const PG8_LAS bf16x8*)(lds + PG8_SB(b, h) + boff + n * 2048 + k * 1024); } while (0)
; #define PG8_MMA(ai, bj, At, Bt) do { __builtin_amdgcn_s_setprio(1); _Pragma("unroll") for (int m = 0; m < 4; ++m) _Pragma("unroll") for (int n = 0; n < 2; ++n) _Pragma("unroll") for (int k = 0; k < 2; ++k) \
;         acc[ai][bj][m][n] = __builtin_amdgcn_mfma_f32_16x16x32_bf16(Bt[n][k], At[m][k], acc[ai][bj][m][n], 0, 0, 0); __builtin_amdgcn_s_setprio(0); } while (0)
; #define PG8_WAIT_V(n) asm volatile("s_waitcnt vmcnt(" #n ")" ::: "memory")
; #define PG8_WAIT_L(n) asm volatile("s_waitcnt lgkmcnt(" #n ")" ::: "memory")
; #define PG8_BAR __builtin_amdgcn_s_barrier()
; #define PG8_SCHED __builtin_amdgcn_sched_barrier(0)
; template <class Epi, class Sched, bool ALIGN_EPI = false, bool SP2 = false>
; __device__ __forceinline__ void gemm_phase(PG8_LAS unsigned char* lds, const Gemm g, const Sched& S, const Epi& E, const int wid_) {
;     ...
;             PG8_LDB(B0, 0, 0); PG8_LDB(B1, 0, 1); PG8_SCHED; PG8_LDA(At, 0, 0); PG8_STAGE(PG8_SA(1, 1), a1 + hstepA, voffA);
;             PG8_WAIT_V(8); PG8_WAIT_L(0); PG8_BAR; PG8_MMA(0, 0, At, B0); PG8_MMA(0, 1, At, B1); PG8_BAR; PG8_SCHED;
;             PG8_LDA(At, 0, 1); PG8_STAGE(PG8_SB(0, 0), b2, voffB); PG8_STAGE(PG8_SB(0, 1), b2 + hstepB, voffB); PG8_STAGE(PG8_SA(0, 0), a2, voffA);
;             PG8_WAIT_V(8); PG8_WAIT_L(0); PG8_BAR; PG8_MMA(1, 0, At, B0); PG8_MMA(1, 1, At, B1); PG8_BAR; PG8_SCHED;
;             PG8_LDB(B0, 1, 0); PG8_LDB(B1, 1, 1); PG8_SCHED; PG8_LDA(At, 1, 0); PG8_STAGE(PG8_SA(0, 1), a2 + hstepA, voffA);
.LBB0_380:
	s_add_i32 s97, s38, 2
	s_add_u32 s98, s6, 0x80
	s_addc_u32 s39, s7, 0
	s_cmp_eq_u32 s41, s38
	s_cselect_b32 s39, s47, s39
	s_cselect_b32 s38, s46, s98
	s_cselect_b32 s99, s61, s62
	s_cselect_b32 s98, s60, s49
	s_add_i32 vcc_lo, 0, 0x14000
	v_add_u32_e32 v164, s42, v180
	v_add_u32_e32 v176, vcc_lo, v180
	ds_read_b128 v[128:131], v164
	ds_read_b128 v[132:135], v164 offset:1024
	ds_read_b128 v[136:139], v164 offset:2048
	ds_read_b128 v[164:167], v164 offset:3072
	ds_read_b128 v[168:171], v176
	ds_read_b128 v[172:175], v176 offset:1024
	ds_read_b128 v[182:185], v176 offset:2048
	ds_read_b128 v[186:189], v176 offset:3072
	v_lshl_add_u64 v[178:179], s[6:7], 0, v[162:163]
	s_add_i32 m0, s36, 0xc000
	ds_read_b128 v[190:193], v181
	ds_read_b128 v[194:197], v181 offset:1024
	ds_read_b128 v[198:201], v181 offset:2048
	ds_read_b128 v[202:205], v181 offset:3072
	ds_read_b128 v[206:209], v181 offset:4096
	ds_read_b128 v[212:215], v181 offset:5120
	ds_read_b128 v[216:219], v181 offset:6144
	ds_read_b128 v[220:223], v181 offset:7168
	global_load_lds_dwordx4 v[178:179], off
	v_lshl_add_u64 v[178:179], s[6:7], 0, v[160:161]
	s_add_i32 m0, s36, 0xe000
	s_nop 0
	global_load_lds_dwordx4 v[178:179], off
	s_waitcnt vmcnt(8)
	s_waitcnt lgkmcnt(0)
	s_barrier
	v_mfma_f32_16x16x32_bf16 v[124:127], v[128:131], v[190:193], v[124:127]
	v_mfma_f32_16x16x32_bf16 v[120:123], v[136:139], v[190:193], v[120:123]
	v_mfma_f32_16x16x32_bf16 v[116:119], v[128:131], v[198:201], v[116:119]
	v_mfma_f32_16x16x32_bf16 v[112:115], v[136:139], v[198:201], v[112:115]
	v_mfma_f32_16x16x32_bf16 v[100:103], v[128:131], v[206:209], v[100:103]
	v_mfma_f32_16x16x32_bf16 v[96:99], v[136:139], v[206:209], v[96:99]
	v_mfma_f32_16x16x32_bf16 v[84:87], v[128:131], v[216:219], v[84:87]
	v_mfma_f32_16x16x32_bf16 v[80:83], v[136:139], v[216:219], v[80:83]
	v_mfma_f32_16x16x32_bf16 v[124:127], v[132:135], v[194:197], v[124:127]
	v_mfma_f32_16x16x32_bf16 v[120:123], v[164:167], v[194:197], v[120:123]
	v_mfma_f32_16x16x32_bf16 v[116:119], v[132:135], v[202:205], v[116:119]
	v_mfma_f32_16x16x32_bf16 v[112:115], v[164:167], v[202:205], v[112:115]
	v_mfma_f32_16x16x32_bf16 v[100:103], v[132:135], v[212:215], v[100:103]
	v_mfma_f32_16x16x32_bf16 v[96:99], v[164:167], v[212:215], v[96:99]
	v_mfma_f32_16x16x32_bf16 v[84:87], v[132:135], v[220:223], v[84:87]
	v_mfma_f32_16x16x32_bf16 v[80:83], v[164:167], v[220:223], v[80:83]
	v_mfma_f32_16x16x32_bf16 v[108:111], v[168:171], v[190:193], v[108:111]
	v_mfma_f32_16x16x32_bf16 v[104:107], v[182:185], v[190:193], v[104:107]
	v_mfma_f32_16x16x32_bf16 v[92:95], v[168:171], v[198:201], v[92:95]
	v_mfma_f32_16x16x32_bf16 v[88:91], v[182:185], v[198:201], v[88:91]
	v_mfma_f32_16x16x32_bf16 v[76:79], v[168:171], v[206:209], v[76:79]
	v_mfma_f32_16x16x32_bf16 v[72:75], v[182:185], v[206:209], v[72:75]
	v_mfma_f32_16x16x32_bf16 v[68:71], v[168:171], v[216:219], v[68:71]
	v_mfma_f32_16x16x32_bf16 v[64:67], v[182:185], v[216:219], v[64:67]
	v_mfma_f32_16x16x32_bf16 v[108:111], v[172:175], v[194:197], v[108:111]
	v_mfma_f32_16x16x32_bf16 v[104:107], v[186:189], v[194:197], v[104:107]
	v_mfma_f32_16x16x32_bf16 v[92:95], v[172:175], v[202:205], v[92:95]
	v_mfma_f32_16x16x32_bf16 v[88:91], v[186:189], v[202:205], v[88:91]
	v_mfma_f32_16x16x32_bf16 v[76:79], v[172:175], v[212:215], v[76:79]
	v_mfma_f32_16x16x32_bf16 v[72:75], v[186:189], v[212:215], v[72:75]
	v_mfma_f32_16x16x32_bf16 v[68:71], v[172:175], v[220:223], v[68:71]
	v_mfma_f32_16x16x32_bf16 v[64:67], v[186:189], v[220:223], v[64:67]
	s_barrier
	s_add_i32 vcc_hi, s42, s83
	v_lshl_add_u64 v[178:179], s[98:99], 0, v[142:143]
	s_mov_b32 m0, vcc_hi
	ds_read_b128 v[190:193], v181 offset:16384
	ds_read_b128 v[194:197], v181 offset:17408
	ds_read_b128 v[198:201], v181 offset:18432
	ds_read_b128 v[202:205], v181 offset:19456
	ds_read_b128 v[206:209], v181 offset:20480
	ds_read_b128 v[212:215], v181 offset:21504
	ds_read_b128 v[216:219], v181 offset:22528
	ds_read_b128 v[220:223], v181 offset:23552
	global_load_lds_dwordx4 v[178:179], off
	s_add_i32 m0, vcc_hi, 0x2000
	v_lshl_add_u64 v[224:225], s[98:99], 0, v[146:147]
	s_add_u32 s98, s98, s18
	s_addc_u32 s99, s99, 0
	s_add_i32 vcc_lo, vcc_lo, s83
	global_load_lds_dwordx4 v[224:225], off
	v_lshl_add_u64 v[226:227], s[98:99], 0, v[142:143]
	s_mov_b32 m0, vcc_lo
	v_lshl_add_u64 v[228:229], s[98:99], 0, v[146:147]
	global_load_lds_dwordx4 v[226:227], off
	s_add_i32 m0, vcc_lo, 0x2000
	v_lshl_add_u64 v[230:231], s[38:39], 0, v[140:141]
	global_load_lds_dwordx4 v[228:229], off
	s_mov_b32 m0, s36
	v_lshl_add_u64 v[232:233], s[38:39], 0, v[144:145]
	global_load_lds_dwordx4 v[230:231], off
	s_mov_b32 m0, s10
	s_nop 0
	global_load_lds_dwordx4 v[232:233], off
	s_waitcnt vmcnt(8)
	s_waitcnt lgkmcnt(0)
	s_barrier
; #define PG8_STAGE(bufoff, gbase, voff) do { _Pragma("unroll") for (int _i = 0; _i < 2; ++_i) \
;         __builtin_amdgcn_global_load_lds((const unsigned*)((const char*)(gbase) + (voff)[_i]), (PG8_LAS unsigned*)(lds + (bufoff) + ldsw + _i * 8192), 16, 0, 0); } while (0)
; #define PG8_LDA(dst, b, h) do { _Pragma("unroll") for (int m = 0; m < 4; ++m) _Pragma("unroll") for (int k = 0; k < 2; ++k) dst[m][k] = *(const PG8_LAS bf16x8*)(lds + PG8_SA(b, h) + aoff + m * 2048 + k * 1024); } while (0)
; #define PG8_LDB(dst, b, h) do { _Pragma("unroll") for (int n = 0; n < 2; ++n) _Pragma("unroll") for (int k = 0; k < 2; ++k) dst[n][k] = *(const PG8_LAS bf16x8*)(lds + PG8_SB(b, h) + boff + n * 2048 + k * 1024); } while (0)
; #define PG8_MMA(ai, bj, At, Bt) do { __builtin_amdgcn_s_setprio(1); _Pragma("unroll") for (int m = 0; m < 4; ++m) _Pragma("unroll") for (int n = 0; n < 2; ++n) _Pragma("unroll") for (int k = 0; k < 2; ++k) \
;         acc[ai][bj][m][n] = __builtin_amdgcn_mfma_f32_16x16x32_bf16(Bt[n][k], At[m][k], acc[ai][bj][m][n], 0, 0, 0); __builtin_amdgcn_s_setprio(0); } while (0)
; #define PG8_WAIT_V(n) asm volatile("s_waitcnt vmcnt(" #n ")" ::: "memory")
; #define PG8_WAIT_L(n) asm volatile("s_waitcnt lgkmcnt(" #n ")" ::: "memory")
; #define PG8_BAR __builtin_amdgcn_s_barrier()
; #define PG8_SCHED __builtin_amdgcn_sched_barrier(0)
; template <class Epi, class Sched, bool ALIGN_EPI = false, bool SP2 = false>
; __device__ __forceinline__ void gemm_phase(PG8_LAS unsigned char* lds, const Gemm g, const Sched& S, const Epi& E, const int wid_) {
;     ...
;             PG8_WAIT_V(8); PG8_WAIT_L(0); PG8_BAR; PG8_MMA(1, 0, At, B0); PG8_MMA(1, 1, At, B1); PG8_BAR; PG8_SCHED;
;             PG8_LDB(B0, 1, 0); PG8_LDB(B1, 1, 1); PG8_SCHED; PG8_LDA(At, 1, 0); PG8_STAGE(PG8_SA(0, 1), a2 + hstepA, voffA);
;             PG8_WAIT_V(8); PG8_WAIT_L(0); PG8_BAR; PG8_MMA(0, 0, At, B0); PG8_MMA(0, 1, At, B1); PG8_BAR; PG8_SCHED;
;             PG8_LDA(At, 1, 1); PG8_STAGE(PG8_SB(1, 0), b3, voffB); PG8_STAGE(PG8_SB(1, 1), b3 + hstepB, voffB); PG8_STAGE(PG8_SA(1, 0), a3, voffA);
	v_mfma_f32_16x16x32_bf16 v[60:63], v[128:131], v[190:193], v[60:63]
	v_mfma_f32_16x16x32_bf16 v[56:59], v[136:139], v[190:193], v[56:59]
	v_mfma_f32_16x16x32_bf16 v[52:55], v[128:131], v[198:201], v[52:55]
	v_mfma_f32_16x16x32_bf16 v[48:51], v[136:139], v[198:201], v[48:51]
	v_mfma_f32_16x16x32_bf16 v[36:39], v[128:131], v[206:209], v[36:39]
	v_mfma_f32_16x16x32_bf16 v[32:35], v[136:139], v[206:209], v[32:35]
	v_mfma_f32_16x16x32_bf16 v[20:23], v[128:131], v[216:219], v[20:23]
	v_mfma_f32_16x16x32_bf16 v[16:19], v[136:139], v[216:219], v[16:19]
	v_mfma_f32_16x16x32_bf16 v[60:63], v[132:135], v[194:197], v[60:63]
	v_mfma_f32_16x16x32_bf16 v[56:59], v[164:167], v[194:197], v[56:59]
	v_mfma_f32_16x16x32_bf16 v[52:55], v[132:135], v[202:205], v[52:55]
	v_mfma_f32_16x16x32_bf16 v[48:51], v[164:167], v[202:205], v[48:51]
	v_mfma_f32_16x16x32_bf16 v[36:39], v[132:135], v[212:215], v[36:39]
	v_mfma_f32_16x16x32_bf16 v[32:35], v[164:167], v[212:215], v[32:35]
	v_mfma_f32_16x16x32_bf16 v[20:23], v[132:135], v[220:223], v[20:23]
	v_mfma_f32_16x16x32_bf16 v[16:19], v[164:167], v[220:223], v[16:19]
	v_mfma_f32_16x16x32_bf16 v[44:47], v[168:171], v[190:193], v[44:47]
	v_mfma_f32_16x16x32_bf16 v[40:43], v[182:185], v[190:193], v[40:43]
	v_mfma_f32_16x16x32_bf16 v[28:31], v[168:171], v[198:201], v[28:31]
	v_mfma_f32_16x16x32_bf16 v[24:27], v[182:185], v[198:201], v[24:27]
	v_mfma_f32_16x16x32_bf16 v[12:15], v[168:171], v[206:209], v[12:15]
	v_mfma_f32_16x16x32_bf16 v[8:11], v[182:185], v[206:209], v[8:11]
	v_mfma_f32_16x16x32_bf16 v[4:7], v[168:171], v[216:219], v[4:7]
	v_mfma_f32_16x16x32_bf16 v[0:3], v[182:185], v[216:219], v[0:3]
	v_mfma_f32_16x16x32_bf16 v[44:47], v[172:175], v[194:197], v[44:47]
	v_mfma_f32_16x16x32_bf16 v[40:43], v[186:189], v[194:197], v[40:43]
	v_mfma_f32_16x16x32_bf16 v[28:31], v[172:175], v[202:205], v[28:31]
	v_mfma_f32_16x16x32_bf16 v[24:27], v[186:189], v[202:205], v[24:27]
	v_mfma_f32_16x16x32_bf16 v[12:15], v[172:175], v[212:215], v[12:15]
	v_mfma_f32_16x16x32_bf16 v[8:11], v[186:189], v[212:215], v[8:11]
	v_mfma_f32_16x16x32_bf16 v[4:7], v[172:175], v[220:223], v[4:7]
	v_mfma_f32_16x16x32_bf16 v[0:3], v[186:189], v[220:223], v[0:3]
	s_barrier
	s_add_i32 s98, 0, 0x18000
	s_add_i32 s99, 0, 0x1c000
	v_add_u32_e32 v164, s98, v180
	v_add_u32_e32 v176, s99, v180
	ds_read_b128 v[128:131], v164
	ds_read_b128 v[132:135], v164 offset:1024
	ds_read_b128 v[136:139], v164 offset:2048
	ds_read_b128 v[164:167], v164 offset:3072
	ds_read_b128 v[168:171], v176
	ds_read_b128 v[172:175], v176 offset:1024
	ds_read_b128 v[182:185], v176 offset:2048
	ds_read_b128 v[186:189], v176 offset:3072
	s_add_u32 s38, s38, s88
	s_addc_u32 s39, s39, 0
	s_mov_b32 m0, s11
	v_lshl_add_u64 v[234:235], s[38:39], 0, v[140:141]
	ds_read_b128 v[190:193], v181 offset:32768
	ds_read_b128 v[194:197], v181 offset:33792
	ds_read_b128 v[198:201], v181 offset:34816
	ds_read_b128 v[202:205], v181 offset:35840
	ds_read_b128 v[206:209], v181 offset:36864
	ds_read_b128 v[212:215], v181 offset:37888
	ds_read_b128 v[216:219], v181 offset:38912
	ds_read_b128 v[220:223], v181 offset:39936
	global_load_lds_dwordx4 v[234:235], off
	v_lshl_add_u64 v[234:235], s[38:39], 0, v[144:145]
	s_mov_b32 m0, s55
	s_nop 0
	global_load_lds_dwordx4 v[234:235], off
	s_waitcnt vmcnt(8)
	s_waitcnt lgkmcnt(0)
	s_barrier
	v_mfma_f32_16x16x32_bf16 v[124:127], v[128:131], v[190:193], v[124:127]
	v_mfma_f32_16x16x32_bf16 v[120:123], v[136:139], v[190:193], v[120:123]
	v_mfma_f32_16x16x32_bf16 v[116:119], v[128:131], v[198:201], v[116:119]
	v_mfma_f32_16x16x32_bf16 v[112:115], v[136:139], v[198:201], v[112:115]
	v_mfma_f32_16x16x32_bf16 v[100:103], v[128:131], v[206:209], v[100:103]
	v_mfma_f32_16x16x32_bf16 v[96:99], v[136:139], v[206:209], v[96:99]
	v_mfma_f32_16x16x32_bf16 v[84:87], v[128:131], v[216:219], v[84:87]
	v_mfma_f32_16x16x32_bf16 v[80:83], v[136:139], v[216:219], v[80:83]
	v_mfma_f32_16x16x32_bf16 v[124:127], v[132:135], v[194:197], v[124:127]
	v_mfma_f32_16x16x32_bf16 v[120:123], v[164:167], v[194:197], v[120:123]
	v_mfma_f32_16x16x32_bf16 v[116:119], v[132:135], v[202:205], v[116:119]
	v_mfma_f32_16x16x32_bf16 v[112:115], v[164:167], v[202:205], v[112:115]
	v_mfma_f32_16x16x32_bf16 v[100:103], v[132:135], v[212:215], v[100:103]
	v_mfma_f32_16x16x32_bf16 v[96:99], v[164:167], v[212:215], v[96:99]
	v_mfma_f32_16x16x32_bf16 v[84:87], v[132:135], v[220:223], v[84:87]
	v_mfma_f32_16x16x32_bf16 v[80:83], v[164:167], v[220:223], v[80:83]
	v_mfma_f32_16x16x32_bf16 v[108:111], v[168:171], v[190:193], v[108:111]
	v_mfma_f32_16x16x32_bf16 v[104:107], v[182:185], v[190:193], v[104:107]
	v_mfma_f32_16x16x32_bf16 v[92:95], v[168:171], v[198:201], v[92:95]
	v_mfma_f32_16x16x32_bf16 v[88:91], v[182:185], v[198:201], v[88:91]
	v_mfma_f32_16x16x32_bf16 v[76:79], v[168:171], v[206:209], v[76:79]
	v_mfma_f32_16x16x32_bf16 v[72:75], v[182:185], v[206:209], v[72:75]
	v_mfma_f32_16x16x32_bf16 v[68:71], v[168:171], v[216:219], v[68:71]
	v_mfma_f32_16x16x32_bf16 v[64:67], v[182:185], v[216:219], v[64:67]
	v_mfma_f32_16x16x32_bf16 v[108:111], v[172:175], v[194:197], v[108:111]
	v_mfma_f32_16x16x32_bf16 v[104:107], v[186:189], v[194:197], v[104:107]
	v_mfma_f32_16x16x32_bf16 v[92:95], v[172:175], v[202:205], v[92:95]
	v_mfma_f32_16x16x32_bf16 v[88:91], v[186:189], v[202:205], v[88:91]
	v_mfma_f32_16x16x32_bf16 v[76:79], v[172:175], v[212:215], v[76:79]
	v_mfma_f32_16x16x32_bf16 v[72:75], v[186:189], v[212:215], v[72:75]
	v_mfma_f32_16x16x32_bf16 v[68:71], v[172:175], v[220:223], v[68:71]
	v_mfma_f32_16x16x32_bf16 v[64:67], v[186:189], v[220:223], v[64:67]
	s_barrier
; #define PG8_STAGE(bufoff, gbase, voff) do { _Pragma("unroll") for (int _i = 0; _i < 2; ++_i) \
;         __builtin_amdgcn_global_load_lds((const unsigned*)((const char*)(gbase) + (voff)[_i]), (PG8_LAS unsigned*)(lds + (bufoff) + ldsw + _i * 8192), 16, 0, 0); } while (0)
; #define PG8_LDA(dst, b, h) do { _Pragma("unroll") for (int m = 0; m < 4; ++m) _Pragma("unroll") for (int k = 0; k < 2; ++k) dst[m][k] = *(const PG8_LAS bf16x8*)(lds + PG8_SA(b, h) + aoff + m * 2048 + k * 1024); } while (0)
; #define PG8_MMA(ai, bj, At, Bt) do { __builtin_amdgcn_s_setprio(1); _Pragma("unroll") for (int m = 0; m < 4; ++m) _Pragma("unroll") for (int n = 0; n < 2; ++n) _Pragma("unroll") for (int k = 0; k < 2; ++k) \
;         acc[ai][bj][m][n] = __builtin_amdgcn_mfma_f32_16x16x32_bf16(Bt[n][k], At[m][k], acc[ai][bj][m][n], 0, 0, 0); __builtin_amdgcn_s_setprio(0); } while (0)
; #define PG8_WAIT_V(n) asm volatile("s_waitcnt vmcnt(" #n ")" ::: "memory")
; #define PG8_WAIT_L(n) asm volatile("s_waitcnt lgkmcnt(" #n ")" ::: "memory")
; #define PG8_BAR __builtin_amdgcn_s_barrier()
; #define PG8_SCHED __builtin_amdgcn_sched_barrier(0)
; template <class Epi, class Sched, bool ALIGN_EPI = false, bool SP2 = false>
; __device__ __forceinline__ void gemm_phase(PG8_LAS unsigned char* lds, const Gemm g, const Sched& S, const Epi& E, const int wid_) {
;     ...
;             PG8_LDA(At, 1, 1); PG8_STAGE(PG8_SB(1, 0), b3, voffB); PG8_STAGE(PG8_SB(1, 1), b3 + hstepB, voffB); PG8_STAGE(PG8_SA(1, 0), a3, voffA);
;             PG8_WAIT_V(8); PG8_WAIT_L(0); PG8_BAR; PG8_MMA(1, 0, At, B0); PG8_MMA(1, 1, At, B1); PG8_BAR; PG8_SCHED;
;     ...
;         if constexpr (ALIGN_EPI) { if (wr == 0) PG8_BAR; }
;         if constexpr (!Epi::AFTER_DRAIN) { E(acc, cur, wr, wc, fr, fq); S.done(cur); }
;         if (!has_next) break;
	s_add_i32 s38, s98, s83
	v_lshl_add_u64 v[178:179], v[178:179], 0, s[66:67]
	s_mov_b32 m0, s38
	ds_read_b128 v[190:193], v181 offset:49152
	ds_read_b128 v[194:197], v181 offset:50176
	ds_read_b128 v[198:201], v181 offset:51200
	ds_read_b128 v[202:205], v181 offset:52224
	ds_read_b128 v[206:209], v181 offset:53248
	ds_read_b128 v[212:215], v181 offset:54272
	ds_read_b128 v[216:219], v181 offset:55296
	ds_read_b128 v[220:223], v181 offset:56320
	global_load_lds_dwordx4 v[178:179], off
	v_lshl_add_u64 v[178:179], v[224:225], 0, s[66:67]
	s_add_i32 m0, s38, 0x2000
	s_add_i32 s38, s99, s83
	global_load_lds_dwordx4 v[178:179], off
	v_lshl_add_u64 v[178:179], v[226:227], 0, s[66:67]
	s_mov_b32 m0, s38
	s_nop 0
	global_load_lds_dwordx4 v[178:179], off
	v_lshl_add_u64 v[178:179], v[228:229], 0, s[66:67]
	s_add_i32 m0, s38, 0x2000
	s_nop 0
	global_load_lds_dwordx4 v[178:179], off
	v_lshl_add_u64 v[178:179], v[230:231], 0, s[66:67]
	s_mov_b32 m0, s33
	s_nop 0
	global_load_lds_dwordx4 v[178:179], off
	v_lshl_add_u64 v[178:179], v[232:233], 0, s[66:67]
	s_mov_b32 m0, s52
	s_nop 0
	global_load_lds_dwordx4 v[178:179], off
	s_waitcnt vmcnt(8)
	s_waitcnt lgkmcnt(0)
	s_barrier
	v_mfma_f32_16x16x32_bf16 v[60:63], v[128:131], v[190:193], v[60:63]
	v_mfma_f32_16x16x32_bf16 v[56:59], v[136:139], v[190:193], v[56:59]
	v_mfma_f32_16x16x32_bf16 v[52:55], v[128:131], v[198:201], v[52:55]
	v_mfma_f32_16x16x32_bf16 v[48:51], v[136:139], v[198:201], v[48:51]
	v_mfma_f32_16x16x32_bf16 v[36:39], v[128:131], v[206:209], v[36:39]
	v_mfma_f32_16x16x32_bf16 v[32:35], v[136:139], v[206:209], v[32:35]
	v_mfma_f32_16x16x32_bf16 v[20:23], v[128:131], v[216:219], v[20:23]
	v_mfma_f32_16x16x32_bf16 v[16:19], v[136:139], v[216:219], v[16:19]
	v_mfma_f32_16x16x32_bf16 v[60:63], v[132:135], v[194:197], v[60:63]
	v_mfma_f32_16x16x32_bf16 v[56:59], v[164:167], v[194:197], v[56:59]
	v_mfma_f32_16x16x32_bf16 v[52:55], v[132:135], v[202:205], v[52:55]
	v_mfma_f32_16x16x32_bf16 v[48:51], v[164:167], v[202:205], v[48:51]
	v_mfma_f32_16x16x32_bf16 v[36:39], v[132:135], v[212:215], v[36:39]
	v_mfma_f32_16x16x32_bf16 v[32:35], v[164:167], v[212:215], v[32:35]
	v_mfma_f32_16x16x32_bf16 v[20:23], v[132:135], v[220:223], v[20:23]
	v_mfma_f32_16x16x32_bf16 v[16:19], v[164:167], v[220:223], v[16:19]
	v_mfma_f32_16x16x32_bf16 v[44:47], v[168:171], v[190:193], v[44:47]
	v_mfma_f32_16x16x32_bf16 v[40:43], v[182:185], v[190:193], v[40:43]
	v_mfma_f32_16x16x32_bf16 v[28:31], v[168:171], v[198:201], v[28:31]
	v_mfma_f32_16x16x32_bf16 v[24:27], v[182:185], v[198:201], v[24:27]
	v_mfma_f32_16x16x32_bf16 v[12:15], v[168:171], v[206:209], v[12:15]
	v_mfma_f32_16x16x32_bf16 v[8:11], v[182:185], v[206:209], v[8:11]
	v_mfma_f32_16x16x32_bf16 v[4:7], v[168:171], v[216:219], v[4:7]
	v_mfma_f32_16x16x32_bf16 v[0:3], v[182:185], v[216:219], v[0:3]
	v_mfma_f32_16x16x32_bf16 v[44:47], v[172:175], v[194:197], v[44:47]
	v_mfma_f32_16x16x32_bf16 v[40:43], v[186:189], v[194:197], v[40:43]
	v_mfma_f32_16x16x32_bf16 v[28:31], v[172:175], v[202:205], v[28:31]
	v_mfma_f32_16x16x32_bf16 v[24:27], v[186:189], v[202:205], v[24:27]
	v_mfma_f32_16x16x32_bf16 v[12:15], v[172:175], v[212:215], v[12:15]
	v_mfma_f32_16x16x32_bf16 v[8:11], v[186:189], v[212:215], v[8:11]
	v_mfma_f32_16x16x32_bf16 v[4:7], v[172:175], v[220:223], v[4:7]
	v_mfma_f32_16x16x32_bf16 v[0:3], v[186:189], v[220:223], v[0:3]
	s_barrier
	s_add_u32 s49, s49, 0x100
	s_addc_u32 s62, s62, 0
	s_add_u32 s6, s6, 0x100
	s_addc_u32 s7, s7, 0
	s_cmp_ge_u32 s97, s71
	s_mov_b32 s38, s97
	s_cbranch_scc0 .LBB0_380
	s_setprio 0
	s_and_b64 vcc, exec, s[94:95]
	s_cbranch_vccz .LBB0_384
	s_barrier
	v_lshl_add_u32 v164, s48, 8, v153
	s_cmp_lt_i32 s37, 2
	s_mov_b64 s[6:7], -1
	s_cbranch_scc0 .LBB0_385

; #define PG8_STAGE(bufoff, gbase, voff) do { _Pragma("unroll") for (int _i = 0; _i < 2; ++_i) \
;         __builtin_amdgcn_global_load_lds((const unsigned*)((const char*)(gbase) + (voff)[_i]), (PG8_LAS unsigned*)(lds + (bufoff) + ldsw + _i * 8192), 16, 0, 0); } while (0)
; #define PG8_LDA(dst, b, h) do { _Pragma("unroll") for (int m = 0; m < 4; ++m) _Pragma("unroll") for (int k = 0; k < 2; ++k) dst[m][k] = *(const PG8_LAS bf16x8*)(lds + PG8_SA(b, h) + aoff + m * 2048 + k * 1024); } while (0)
; #define PG8_LDB(dst, b, h) do { _Pragma("unroll") for (int n = 0; n < 2; ++n) _Pragma("unroll") for (int k = 0; k < 2; ++k) dst[n][k] = *(const PG8_LAS bf16x8*)(lds + PG8_SB(b, h) + boff + n * 2048 + k * 1024); } while (0)
; #define PG8_MMA(ai, bj, At, Bt) do { __builtin_amdgcn_s_setprio(1); _Pragma("unroll") for (int m = 0; m < 4; ++m) _Pragma("unroll") for (int n = 0; n < 2; ++n) _Pragma("unroll") for (int k = 0; k < 2; ++k) \
;         acc[ai][bj][m][n] = __builtin_amdgcn_mfma_f32_16x16x32_bf16(Bt[n][k], At[m][k], acc[ai][bj][m][n], 0, 0, 0); __builtin_amdgcn_s_setprio(0); } while (0)
; #define PG8_WAIT_V(n) asm volatile("s_waitcnt vmcnt(" #n ")" ::: "memory")
; #define PG8_BAR __builtin_amdgcn_s_barrier()
; template <class Epi, class Sched, bool ALIGN_EPI = false, bool SP2 = false>
; __device__ __forceinline__ void gemm_phase(PG8_LAS unsigned char* lds, const Gemm g, const Sched& S, const Epi& E, const int wid_) {
;     ...
;         for (int t = 0; t < nt; t += 2) {
;             const bool last = (t == nt - 2);
;             const char* a1 = cA + (size_t)(t + 1) * kstep;
;             const char* a2 = last ? nA : cA + (size_t)(t + 2) * kstep; const char* b2 = last ? nB : cB + (size_t)(t + 2) * kstep;
;             const char* a3 = a2 + kstep; const char* b3 = b2 + kstep;
;             if (last && has_next) S.a_ready(nxt);
;             if constexpr (SP2) {
;             PG8_LDB(B0, 0, 0); PG8_LDB(B1, 0, 1); PG8_SCHED; PG8_LDA(At, 0, 0); PG8_STAGE(PG8_SA(1, 1), a1 + hstepA, voffA);
;             PG8_WAIT_V(8); PG8_WAIT_L(0); PG8_BAR; PG8_MMA(0, 0, At, B0); PG8_MMA(0, 1, At, B1); PG8_BAR; PG8_SCHED;
;             PG8_LDA(At, 0, 1); PG8_STAGE(PG8_SB(0, 0), b2, voffB); PG8_STAGE(PG8_SB(0, 1), b2 + hstepB, voffB); PG8_STAGE(PG8_SA(0, 0), a2, voffA);
;             PG8_WAIT_V(8); PG8_WAIT_L(0); PG8_BAR; PG8_MMA(1, 0, At, B0); PG8_MMA(1, 1, At, B1); PG8_BAR; PG8_SCHED;
.LBB0_614:
	s_add_i32 s38, s8, 2
	s_add_u32 s39, s6, 0x80
	s_addc_u32 s9, s7, 0
	s_cmp_eq_u32 s80, s8
	s_cselect_b32 s9, s73, s9
	s_cselect_b32 s8, s72, s39
	s_cselect_b32 s87, s75, s76
	s_cselect_b32 s86, s74, s11
	s_add_i32 s39, 0, 0x14000
	v_add_u32_e32 v132, s42, v246
	v_add_u32_e32 v156, s39, v246
	ds_read_b128 v[104:107], v132
	ds_read_b128 v[112:115], v132 offset:1024
	ds_read_b128 v[124:127], v132 offset:2048
	ds_read_b128 v[132:135], v132 offset:3072
	ds_read_b128 v[144:147], v156
	ds_read_b128 v[148:151], v156 offset:1024
	ds_read_b128 v[152:155], v156 offset:2048
	ds_read_b128 v[156:159], v156 offset:3072
	v_lshl_add_u64 v[194:195], s[6:7], 0, v[216:217]
	s_add_i32 m0, s41, 0xc000
	ds_read_b128 v[160:163], v247
	ds_read_b128 v[164:167], v247 offset:1024
	ds_read_b128 v[168:171], v247 offset:2048
	ds_read_b128 v[172:175], v247 offset:3072
	ds_read_b128 v[178:181], v247 offset:4096
	ds_read_b128 v[182:185], v247 offset:5120
	ds_read_b128 v[186:189], v247 offset:6144
	ds_read_b128 v[190:193], v247 offset:7168
	global_load_lds_dwordx4 v[194:195], off
	v_lshl_add_u64 v[194:195], s[6:7], 0, v[214:215]
	s_add_i32 m0, s41, 0xe000
	s_nop 0
	global_load_lds_dwordx4 v[194:195], off
	s_waitcnt vmcnt(8)
	s_waitcnt lgkmcnt(0)
	s_barrier
	v_mfma_f32_16x16x32_bf16 v[140:143], v[104:107], v[160:163], v[140:143]
	v_mfma_f32_16x16x32_bf16 v[136:139], v[124:127], v[160:163], v[136:139]
	v_mfma_f32_16x16x32_bf16 v[116:119], v[104:107], v[168:171], v[116:119]
	v_mfma_f32_16x16x32_bf16 v[108:111], v[124:127], v[168:171], v[108:111]
	v_mfma_f32_16x16x32_bf16 v[92:95], v[104:107], v[178:181], v[92:95]
	v_mfma_f32_16x16x32_bf16 v[88:91], v[124:127], v[178:181], v[88:91]
	v_mfma_f32_16x16x32_bf16 v[76:79], v[104:107], v[186:189], v[76:79]
	v_mfma_f32_16x16x32_bf16 v[72:75], v[124:127], v[186:189], v[72:75]
	v_mfma_f32_16x16x32_bf16 v[140:143], v[112:115], v[164:167], v[140:143]
	v_mfma_f32_16x16x32_bf16 v[136:139], v[132:135], v[164:167], v[136:139]
	v_mfma_f32_16x16x32_bf16 v[116:119], v[112:115], v[172:175], v[116:119]
	v_mfma_f32_16x16x32_bf16 v[108:111], v[132:135], v[172:175], v[108:111]
	v_mfma_f32_16x16x32_bf16 v[92:95], v[112:115], v[182:185], v[92:95]
	v_mfma_f32_16x16x32_bf16 v[88:91], v[132:135], v[182:185], v[88:91]
	v_mfma_f32_16x16x32_bf16 v[76:79], v[112:115], v[190:193], v[76:79]
	v_mfma_f32_16x16x32_bf16 v[72:75], v[132:135], v[190:193], v[72:75]
	v_mfma_f32_16x16x32_bf16 v[128:131], v[144:147], v[160:163], v[128:131]
	v_mfma_f32_16x16x32_bf16 v[120:123], v[152:155], v[160:163], v[120:123]
	v_mfma_f32_16x16x32_bf16 v[100:103], v[144:147], v[168:171], v[100:103]
	v_mfma_f32_16x16x32_bf16 v[96:99], v[152:155], v[168:171], v[96:99]
	v_mfma_f32_16x16x32_bf16 v[84:87], v[144:147], v[178:181], v[84:87]
	v_mfma_f32_16x16x32_bf16 v[80:83], v[152:155], v[178:181], v[80:83]
	v_mfma_f32_16x16x32_bf16 v[68:71], v[144:147], v[186:189], v[68:71]
	v_mfma_f32_16x16x32_bf16 v[64:67], v[152:155], v[186:189], v[64:67]
	v_mfma_f32_16x16x32_bf16 v[128:131], v[148:151], v[164:167], v[128:131]
	v_mfma_f32_16x16x32_bf16 v[120:123], v[156:159], v[164:167], v[120:123]
	v_mfma_f32_16x16x32_bf16 v[100:103], v[148:151], v[172:175], v[100:103]
	v_mfma_f32_16x16x32_bf16 v[96:99], v[156:159], v[172:175], v[96:99]
	v_mfma_f32_16x16x32_bf16 v[84:87], v[148:151], v[182:185], v[84:87]
	v_mfma_f32_16x16x32_bf16 v[80:83], v[156:159], v[182:185], v[80:83]
	v_mfma_f32_16x16x32_bf16 v[68:71], v[148:151], v[190:193], v[68:71]
	v_mfma_f32_16x16x32_bf16 v[64:67], v[156:159], v[190:193], v[64:67]
	s_barrier
	s_add_i32 s85, s42, s33
	v_lshl_add_u64 v[194:195], s[86:87], 0, v[176:177]
	s_mov_b32 m0, s85
	ds_read_b128 v[160:163], v247 offset:16384
	ds_read_b128 v[164:167], v247 offset:17408
	ds_read_b128 v[168:171], v247 offset:18432
	ds_read_b128 v[172:175], v247 offset:19456
	ds_read_b128 v[178:181], v247 offset:20480
	ds_read_b128 v[182:185], v247 offset:21504
	ds_read_b128 v[186:189], v247 offset:22528
	ds_read_b128 v[190:193], v247 offset:23552
	global_load_lds_dwordx4 v[194:195], off
	s_add_i32 m0, s85, 0x2000
	v_lshl_add_u64 v[196:197], s[86:87], 0, v[202:203]
	s_add_u32 s86, s86, s22
	s_addc_u32 s87, s87, 0
	s_add_i32 s39, s39, s33
	global_load_lds_dwordx4 v[196:197], off
	v_lshl_add_u64 v[198:199], s[86:87], 0, v[176:177]
	s_mov_b32 m0, s39
	v_lshl_add_u64 v[200:201], s[86:87], 0, v[202:203]
	global_load_lds_dwordx4 v[198:199], off
	s_add_i32 m0, s39, 0x2000
	v_lshl_add_u64 v[218:219], s[8:9], 0, v[206:207]
	global_load_lds_dwordx4 v[200:201], off
	s_mov_b32 m0, s41
	v_lshl_add_u64 v[220:221], s[8:9], 0, v[204:205]
	global_load_lds_dwordx4 v[218:219], off
	s_mov_b32 m0, s43
	s_nop 0
	global_load_lds_dwordx4 v[220:221], off
	s_waitcnt vmcnt(8)
	s_waitcnt lgkmcnt(0)
	s_barrier
; #define PG8_STAGE(bufoff, gbase, voff) do { _Pragma("unroll") for (int _i = 0; _i < 2; ++_i) \
;         __builtin_amdgcn_global_load_lds((const unsigned*)((const char*)(gbase) + (voff)[_i]), (PG8_LAS unsigned*)(lds + (bufoff) + ldsw + _i * 8192), 16, 0, 0); } while (0)
; #define PG8_LDA(dst, b, h) do { _Pragma("unroll") for (int m = 0; m < 4; ++m) _Pragma("unroll") for (int k = 0; k < 2; ++k) dst[m][k] = *(const PG8_LAS bf16x8*)(lds + PG8_SA(b, h) + aoff + m * 2048 + k * 1024); } while (0)
; #define PG8_LDB(dst, b, h) do { _Pragma("unroll") for (int n = 0; n < 2; ++n) _Pragma("unroll") for (int k = 0; k < 2; ++k) dst[n][k] = *(const PG8_LAS bf16x8*)(lds + PG8_SB(b, h) + boff + n * 2048 + k * 1024); } while (0)
; #define PG8_MMA(ai, bj, At, Bt) do { __builtin_amdgcn_s_setprio(1); _Pragma("unroll") for (int m = 0; m < 4; ++m) _Pragma("unroll") for (int n = 0; n < 2; ++n) _Pragma("unroll") for (int k = 0; k < 2; ++k) \
;         acc[ai][bj][m][n] = __builtin_amdgcn_mfma_f32_16x16x32_bf16(Bt[n][k], At[m][k], acc[ai][bj][m][n], 0, 0, 0); __builtin_amdgcn_s_setprio(0); } while (0)
; #define PG8_WAIT_V(n) asm volatile("s_waitcnt vmcnt(" #n ")" ::: "memory")
; #define PG8_WAIT_L(n) asm volatile("s_waitcnt lgkmcnt(" #n ")" ::: "memory")
; #define PG8_BAR __builtin_amdgcn_s_barrier()
; #define PG8_SCHED __builtin_amdgcn_sched_barrier(0)
; template <class Epi, class Sched, bool ALIGN_EPI = false, bool SP2 = false>
; __device__ __forceinline__ void gemm_phase(PG8_LAS unsigned char* lds, const Gemm g, const Sched& S, const Epi& E, const int wid_) {
;     ...
;             PG8_WAIT_V(8); PG8_WAIT_L(0); PG8_BAR; PG8_MMA(1, 0, At, B0); PG8_MMA(1, 1, At, B1); PG8_BAR; PG8_SCHED;
;             PG8_LDB(B0, 1, 0); PG8_LDB(B1, 1, 1); PG8_SCHED; PG8_LDA(At, 1, 0); PG8_STAGE(PG8_SA(0, 1), a2 + hstepA, voffA);
;             PG8_WAIT_V(8); PG8_WAIT_L(0); PG8_BAR; PG8_MMA(0, 0, At, B0); PG8_MMA(0, 1, At, B1); PG8_BAR; PG8_SCHED;
	v_mfma_f32_16x16x32_bf16 v[60:63], v[104:107], v[160:163], v[60:63]
	v_mfma_f32_16x16x32_bf16 v[56:59], v[124:127], v[160:163], v[56:59]
	v_mfma_f32_16x16x32_bf16 v[44:47], v[104:107], v[168:171], v[44:47]
	v_mfma_f32_16x16x32_bf16 v[40:43], v[124:127], v[168:171], v[40:43]
	v_mfma_f32_16x16x32_bf16 v[28:31], v[104:107], v[178:181], v[28:31]
	v_mfma_f32_16x16x32_bf16 v[24:27], v[124:127], v[178:181], v[24:27]
	v_mfma_f32_16x16x32_bf16 v[12:15], v[104:107], v[186:189], v[12:15]
	v_mfma_f32_16x16x32_bf16 v[8:11], v[124:127], v[186:189], v[8:11]
	v_mfma_f32_16x16x32_bf16 v[60:63], v[112:115], v[164:167], v[60:63]
	v_mfma_f32_16x16x32_bf16 v[56:59], v[132:135], v[164:167], v[56:59]
	v_mfma_f32_16x16x32_bf16 v[44:47], v[112:115], v[172:175], v[44:47]
	v_mfma_f32_16x16x32_bf16 v[40:43], v[132:135], v[172:175], v[40:43]
	v_mfma_f32_16x16x32_bf16 v[28:31], v[112:115], v[182:185], v[28:31]
	v_mfma_f32_16x16x32_bf16 v[24:27], v[132:135], v[182:185], v[24:27]
	v_mfma_f32_16x16x32_bf16 v[12:15], v[112:115], v[190:193], v[12:15]
	v_mfma_f32_16x16x32_bf16 v[8:11], v[132:135], v[190:193], v[8:11]
	v_mfma_f32_16x16x32_bf16 v[52:55], v[144:147], v[160:163], v[52:55]
	v_mfma_f32_16x16x32_bf16 v[48:51], v[152:155], v[160:163], v[48:51]
	v_mfma_f32_16x16x32_bf16 v[36:39], v[144:147], v[168:171], v[36:39]
	v_mfma_f32_16x16x32_bf16 v[32:35], v[152:155], v[168:171], v[32:35]
	v_mfma_f32_16x16x32_bf16 v[20:23], v[144:147], v[178:181], v[20:23]
	v_mfma_f32_16x16x32_bf16 v[16:19], v[152:155], v[178:181], v[16:19]
	v_mfma_f32_16x16x32_bf16 v[4:7], v[144:147], v[186:189], v[4:7]
	v_mfma_f32_16x16x32_bf16 v[0:3], v[152:155], v[186:189], v[0:3]
	v_mfma_f32_16x16x32_bf16 v[52:55], v[148:151], v[164:167], v[52:55]
	v_mfma_f32_16x16x32_bf16 v[48:51], v[156:159], v[164:167], v[48:51]
	v_mfma_f32_16x16x32_bf16 v[36:39], v[148:151], v[172:175], v[36:39]
	v_mfma_f32_16x16x32_bf16 v[32:35], v[156:159], v[172:175], v[32:35]
	v_mfma_f32_16x16x32_bf16 v[20:23], v[148:151], v[182:185], v[20:23]
	v_mfma_f32_16x16x32_bf16 v[16:19], v[156:159], v[182:185], v[16:19]
	v_mfma_f32_16x16x32_bf16 v[4:7], v[148:151], v[190:193], v[4:7]
	v_mfma_f32_16x16x32_bf16 v[0:3], v[156:159], v[190:193], v[0:3]
	s_barrier
	s_add_i32 s39, 0, 0x18000
	s_add_i32 s85, 0, 0x1c000
	v_add_u32_e32 v132, s39, v246
	v_add_u32_e32 v156, s85, v246
	ds_read_b128 v[104:107], v132
	ds_read_b128 v[112:115], v132 offset:1024
	ds_read_b128 v[124:127], v132 offset:2048
	ds_read_b128 v[132:135], v132 offset:3072
	ds_read_b128 v[144:147], v156
	ds_read_b128 v[148:151], v156 offset:1024
	ds_read_b128 v[152:155], v156 offset:2048
	ds_read_b128 v[156:159], v156 offset:3072
	s_add_u32 s8, s8, s22
	s_addc_u32 s9, s9, 0
	s_mov_b32 m0, s46
	v_lshl_add_u64 v[222:223], s[8:9], 0, v[206:207]
	ds_read_b128 v[160:163], v247 offset:32768
	ds_read_b128 v[164:167], v247 offset:33792
	ds_read_b128 v[168:171], v247 offset:34816
	ds_read_b128 v[172:175], v247 offset:35840
	ds_read_b128 v[178:181], v247 offset:36864
	ds_read_b128 v[182:185], v247 offset:37888
	ds_read_b128 v[186:189], v247 offset:38912
	ds_read_b128 v[190:193], v247 offset:39936
	global_load_lds_dwordx4 v[222:223], off
	v_lshl_add_u64 v[222:223], s[8:9], 0, v[204:205]
	s_mov_b32 m0, s47
	s_nop 0
	global_load_lds_dwordx4 v[222:223], off
	s_waitcnt vmcnt(8)
	s_waitcnt lgkmcnt(0)
	s_barrier
	v_mfma_f32_16x16x32_bf16 v[140:143], v[104:107], v[160:163], v[140:143]
	v_mfma_f32_16x16x32_bf16 v[136:139], v[124:127], v[160:163], v[136:139]
	v_mfma_f32_16x16x32_bf16 v[116:119], v[104:107], v[168:171], v[116:119]
	v_mfma_f32_16x16x32_bf16 v[108:111], v[124:127], v[168:171], v[108:111]
	v_mfma_f32_16x16x32_bf16 v[92:95], v[104:107], v[178:181], v[92:95]
	v_mfma_f32_16x16x32_bf16 v[88:91], v[124:127], v[178:181], v[88:91]
	v_mfma_f32_16x16x32_bf16 v[76:79], v[104:107], v[186:189], v[76:79]
	v_mfma_f32_16x16x32_bf16 v[72:75], v[124:127], v[186:189], v[72:75]
	v_mfma_f32_16x16x32_bf16 v[140:143], v[112:115], v[164:167], v[140:143]
	v_mfma_f32_16x16x32_bf16 v[136:139], v[132:135], v[164:167], v[136:139]
	v_mfma_f32_16x16x32_bf16 v[116:119], v[112:115], v[172:175], v[116:119]
	v_mfma_f32_16x16x32_bf16 v[108:111], v[132:135], v[172:175], v[108:111]
	v_mfma_f32_16x16x32_bf16 v[92:95], v[112:115], v[182:185], v[92:95]
	v_mfma_f32_16x16x32_bf16 v[88:91], v[132:135], v[182:185], v[88:91]
	v_mfma_f32_16x16x32_bf16 v[76:79], v[112:115], v[190:193], v[76:79]
	v_mfma_f32_16x16x32_bf16 v[72:75], v[132:135], v[190:193], v[72:75]
	v_mfma_f32_16x16x32_bf16 v[128:131], v[144:147], v[160:163], v[128:131]
	v_mfma_f32_16x16x32_bf16 v[120:123], v[152:155], v[160:163], v[120:123]
	v_mfma_f32_16x16x32_bf16 v[100:103], v[144:147], v[168:171], v[100:103]
	v_mfma_f32_16x16x32_bf16 v[96:99], v[152:155], v[168:171], v[96:99]
	v_mfma_f32_16x16x32_bf16 v[84:87], v[144:147], v[178:181], v[84:87]
	v_mfma_f32_16x16x32_bf16 v[80:83], v[152:155], v[178:181], v[80:83]
	v_mfma_f32_16x16x32_bf16 v[68:71], v[144:147], v[186:189], v[68:71]
	v_mfma_f32_16x16x32_bf16 v[64:67], v[152:155], v[186:189], v[64:67]
	v_mfma_f32_16x16x32_bf16 v[128:131], v[148:151], v[164:167], v[128:131]
	v_mfma_f32_16x16x32_bf16 v[120:123], v[156:159], v[164:167], v[120:123]
	v_mfma_f32_16x16x32_bf16 v[100:103], v[148:151], v[172:175], v[100:103]
	v_mfma_f32_16x16x32_bf16 v[96:99], v[156:159], v[172:175], v[96:99]
	v_mfma_f32_16x16x32_bf16 v[84:87], v[148:151], v[182:185], v[84:87]
	v_mfma_f32_16x16x32_bf16 v[80:83], v[156:159], v[182:185], v[80:83]
	v_mfma_f32_16x16x32_bf16 v[68:71], v[148:151], v[190:193], v[68:71]
	v_mfma_f32_16x16x32_bf16 v[64:67], v[156:159], v[190:193], v[64:67]
	s_barrier
; #define PG8_STAGE(bufoff, gbase, voff) do { _Pragma("unroll") for (int _i = 0; _i < 2; ++_i) \
;         __builtin_amdgcn_global_load_lds((const unsigned*)((const char*)(gbase) + (voff)[_i]), (PG8_LAS unsigned*)(lds + (bufoff) + ldsw + _i * 8192), 16, 0, 0); } while (0)
; #define PG8_LDA(dst, b, h) do { _Pragma("unroll") for (int m = 0; m < 4; ++m) _Pragma("unroll") for (int k = 0; k < 2; ++k) dst[m][k] = *(const PG8_LAS bf16x8*)(lds + PG8_SA(b, h) + aoff + m * 2048 + k * 1024); } while (0)
; #define PG8_MMA(ai, bj, At, Bt) do { __builtin_amdgcn_s_setprio(1); _Pragma("unroll") for (int m = 0; m < 4; ++m) _Pragma("unroll") for (int n = 0; n < 2; ++n) _Pragma("unroll") for (int k = 0; k < 2; ++k) \
;         acc[ai][bj][m][n] = __builtin_amdgcn_mfma_f32_16x16x32_bf16(Bt[n][k], At[m][k], acc[ai][bj][m][n], 0, 0, 0); __builtin_amdgcn_s_setprio(0); } while (0)
; #define PG8_WAIT_V(n) asm volatile("s_waitcnt vmcnt(" #n ")" ::: "memory")
; #define PG8_WAIT_L(n) asm volatile("s_waitcnt lgkmcnt(" #n ")" ::: "memory")
; #define PG8_BAR __builtin_amdgcn_s_barrier()
; #define PG8_SCHED __builtin_amdgcn_sched_barrier(0)
; template <class Epi, class Sched, bool ALIGN_EPI = false, bool SP2 = false>
; __device__ __forceinline__ void gemm_phase(PG8_LAS unsigned char* lds, const Gemm g, const Sched& S, const Epi& E, const int wid_) {
;     ...
;             PG8_LDA(At, 1, 1); PG8_STAGE(PG8_SB(1, 0), b3, voffB); PG8_STAGE(PG8_SB(1, 1), b3 + hstepB, voffB); PG8_STAGE(PG8_SA(1, 0), a3, voffA);
;             PG8_WAIT_V(8); PG8_WAIT_L(0); PG8_BAR; PG8_MMA(1, 0, At, B0); PG8_MMA(1, 1, At, B1); PG8_BAR; PG8_SCHED;
;     ...
;         if constexpr (ALIGN_EPI) { if (wr == 0) PG8_BAR; }
;         if constexpr (!Epi::AFTER_DRAIN) { E(acc, cur, wr, wc, fr, fq); S.done(cur); }
;         if (!has_next) break;
	s_add_i32 s8, s39, s33
	v_lshl_add_u64 v[194:195], v[194:195], 0, s[66:67]
	s_mov_b32 m0, s8
	ds_read_b128 v[160:163], v247 offset:49152
	ds_read_b128 v[164:167], v247 offset:50176
	ds_read_b128 v[168:171], v247 offset:51200
	ds_read_b128 v[172:175], v247 offset:52224
	ds_read_b128 v[178:181], v247 offset:53248
	ds_read_b128 v[182:185], v247 offset:54272
	ds_read_b128 v[186:189], v247 offset:55296
	ds_read_b128 v[190:193], v247 offset:56320
	global_load_lds_dwordx4 v[194:195], off
	v_lshl_add_u64 v[194:195], v[196:197], 0, s[66:67]
	s_add_i32 m0, s8, 0x2000
	s_add_i32 s8, s85, s33
	global_load_lds_dwordx4 v[194:195], off
	v_lshl_add_u64 v[194:195], v[198:199], 0, s[66:67]
	s_mov_b32 m0, s8
	s_nop 0
	global_load_lds_dwordx4 v[194:195], off
	v_lshl_add_u64 v[194:195], v[200:201], 0, s[66:67]
	s_add_i32 m0, s8, 0x2000
	s_nop 0
	global_load_lds_dwordx4 v[194:195], off
	v_lshl_add_u64 v[194:195], v[218:219], 0, s[66:67]
	s_mov_b32 m0, s68
	s_nop 0
	global_load_lds_dwordx4 v[194:195], off
	v_lshl_add_u64 v[194:195], v[220:221], 0, s[66:67]
	s_mov_b32 m0, s69
	s_nop 0
	global_load_lds_dwordx4 v[194:195], off
	s_waitcnt vmcnt(8)
	s_waitcnt lgkmcnt(0)
	s_barrier
	v_mfma_f32_16x16x32_bf16 v[60:63], v[104:107], v[160:163], v[60:63]
	v_mfma_f32_16x16x32_bf16 v[56:59], v[124:127], v[160:163], v[56:59]
	v_mfma_f32_16x16x32_bf16 v[44:47], v[104:107], v[168:171], v[44:47]
	v_mfma_f32_16x16x32_bf16 v[40:43], v[124:127], v[168:171], v[40:43]
	v_mfma_f32_16x16x32_bf16 v[28:31], v[104:107], v[178:181], v[28:31]
	v_mfma_f32_16x16x32_bf16 v[24:27], v[124:127], v[178:181], v[24:27]
	v_mfma_f32_16x16x32_bf16 v[12:15], v[104:107], v[186:189], v[12:15]
	v_mfma_f32_16x16x32_bf16 v[8:11], v[124:127], v[186:189], v[8:11]
	v_mfma_f32_16x16x32_bf16 v[60:63], v[112:115], v[164:167], v[60:63]
	v_mfma_f32_16x16x32_bf16 v[56:59], v[132:135], v[164:167], v[56:59]
	v_mfma_f32_16x16x32_bf16 v[44:47], v[112:115], v[172:175], v[44:47]
	v_mfma_f32_16x16x32_bf16 v[40:43], v[132:135], v[172:175], v[40:43]
	v_mfma_f32_16x16x32_bf16 v[28:31], v[112:115], v[182:185], v[28:31]
	v_mfma_f32_16x16x32_bf16 v[24:27], v[132:135], v[182:185], v[24:27]
	v_mfma_f32_16x16x32_bf16 v[12:15], v[112:115], v[190:193], v[12:15]
	v_mfma_f32_16x16x32_bf16 v[8:11], v[132:135], v[190:193], v[8:11]
	v_mfma_f32_16x16x32_bf16 v[52:55], v[144:147], v[160:163], v[52:55]
	v_mfma_f32_16x16x32_bf16 v[48:51], v[152:155], v[160:163], v[48:51]
	v_mfma_f32_16x16x32_bf16 v[36:39], v[144:147], v[168:171], v[36:39]
	v_mfma_f32_16x16x32_bf16 v[32:35], v[152:155], v[168:171], v[32:35]
	v_mfma_f32_16x16x32_bf16 v[20:23], v[144:147], v[178:181], v[20:23]
	v_mfma_f32_16x16x32_bf16 v[16:19], v[152:155], v[178:181], v[16:19]
	v_mfma_f32_16x16x32_bf16 v[4:7], v[144:147], v[186:189], v[4:7]
	v_mfma_f32_16x16x32_bf16 v[0:3], v[152:155], v[186:189], v[0:3]
	v_mfma_f32_16x16x32_bf16 v[52:55], v[148:151], v[164:167], v[52:55]
	v_mfma_f32_16x16x32_bf16 v[48:51], v[156:159], v[164:167], v[48:51]
	v_mfma_f32_16x16x32_bf16 v[36:39], v[148:151], v[172:175], v[36:39]
	v_mfma_f32_16x16x32_bf16 v[32:35], v[156:159], v[172:175], v[32:35]
	v_mfma_f32_16x16x32_bf16 v[20:23], v[148:151], v[182:185], v[20:23]
	v_mfma_f32_16x16x32_bf16 v[16:19], v[156:159], v[182:185], v[16:19]
	v_mfma_f32_16x16x32_bf16 v[4:7], v[148:151], v[190:193], v[4:7]
	v_mfma_f32_16x16x32_bf16 v[0:3], v[156:159], v[190:193], v[0:3]
	s_barrier
	s_add_u32 s11, s11, 0x100
	s_addc_u32 s76, s76, 0
	s_add_u32 s6, s6, 0x100
	s_addc_u32 s7, s7, 0
	s_cmp_ge_u32 s38, s71
	s_mov_b32 s8, s38
	s_cbranch_scc0 .LBB0_614
	s_setprio 0
	s_and_b64 vcc, exec, s[36:37]
	s_cbranch_vccz .LBB0_617
	s_barrier
